# attn main loop re-emitted + s_nop pads replaced by useful fillers
# speedup vs baseline: 1.0334x; 1.0076x over previous
.LBB5_822:
	s_lshl_b32 s24, s34, 1
	v_add_u32_e32 v183, s24, v212
	v_add_u32_e32 v215, s3, v208
	v_add_f32_e32 v251, v80, v81
	v_mfma_f32_32x32x16_bf16 v[112:127], v[172:175], v[236:239], v[220:235]
	s_add_i32 s24, s33, s64
	s_mov_b32 m0, s24
	v_lshl_add_u64 v[248:249], v[198:199], 0, s[36:37]
	global_load_lds_dwordx4 v[248:249], off
	v_add_f32_e32 v251, v82, v251
	v_add_f32_e32 v251, v83, v251
	v_add_f32_e32 v251, v84, v251
	v_add_f32_e32 v251, v85, v251
	v_cvt_pk_bf16_f32 v140, v80, v81
	v_cvt_pk_bf16_f32 v141, v82, v83
	ds_read_b128 v[172:175], v215
	v_mfma_f32_32x32x16_bf16 v[96:111], v[160:163], v[236:239], v[220:235]
	s_lshl_b32 s24, s3, 1
	s_add_i32 s24, s24, s66
	s_mov_b32 m0, s24
	v_lshl_add_u64 v[248:249], v[196:197], 0, s[36:37]
	global_load_lds_dwordx4 v[248:249], off
	v_add_f32_e32 v251, v86, v251
	v_add_f32_e32 v251, v87, v251
	v_add_f32_e32 v251, v88, v251
	v_add_f32_e32 v251, v89, v251
	v_cvt_pk_bf16_f32 v142, v84, v85
	v_cvt_pk_bf16_f32 v143, v86, v87
	ds_read_b128 v[160:163], v215 offset:512
	v_mfma_f32_32x32x16_bf16 v[112:127], v[168:171], v[240:243], v[112:127]
	s_addk_i32 s24, 0x2000
	s_mov_b32 m0, s24
	v_lshl_add_u64 v[248:249], v[194:195], 0, s[36:37]
	global_load_lds_dwordx4 v[248:249], off
	v_add_f32_e32 v251, v90, v251
	v_add_f32_e32 v251, v91, v251
	v_add_f32_e32 v251, v92, v251
	v_add_f32_e32 v251, v93, v251
	v_cvt_pk_bf16_f32 v136, v88, v89
	v_cvt_pk_bf16_f32 v137, v90, v91
	ds_read_b128 v[168:171], v215 offset:2048
	v_mfma_f32_32x32x16_bf16 v[96:111], v[152:155], v[240:243], v[96:111]
	v_add_f32_e32 v251, v94, v251
	v_add_f32_e32 v251, v95, v251
	v_add_f32_e32 v251, v64, v251
	v_add_f32_e32 v251, v65, v251
	v_cvt_pk_bf16_f32 v138, v92, v93
	v_cvt_pk_bf16_f32 v139, v94, v95
	ds_read_b128 v[152:155], v215 offset:2560
	v_mfma_f32_32x32x16_bf16 v[112:127], v[164:167], v[244:247], v[112:127]
	v_add_f32_e32 v251, v66, v251
	v_add_f32_e32 v251, v67, v251
	v_add_f32_e32 v251, v68, v251
	v_add_f32_e32 v251, v69, v251
	v_cvt_pk_bf16_f32 v132, v64, v65
	v_cvt_pk_bf16_f32 v133, v66, v67
	ds_read_b128 v[164:167], v215 offset:4096
	v_mfma_f32_32x32x16_bf16 v[96:111], v[148:151], v[244:247], v[96:111]
	v_add_f32_e32 v251, v70, v251
	v_add_f32_e32 v251, v71, v251
	v_add_f32_e32 v251, v72, v251
	v_add_f32_e32 v251, v73, v251
	v_cvt_pk_bf16_f32 v134, v68, v69
	v_cvt_pk_bf16_f32 v135, v70, v71
	ds_read_b128 v[148:151], v215 offset:4608
	ds_read_b64_tr_b16 v[80:81], v183 offset:24576
	ds_read_b64_tr_b16 v[82:83], v183 offset:25088
	v_mfma_f32_32x32x16_bf16 v[112:127], v[156:159], v[252:255], v[112:127]
	v_add_f32_e32 v251, v74, v251
	v_add_f32_e32 v251, v75, v251
	v_add_f32_e32 v251, v76, v251
	v_add_f32_e32 v251, v77, v251
	v_cvt_pk_bf16_f32 v128, v72, v73
	v_cvt_pk_bf16_f32 v129, v74, v75
	ds_read_b128 v[156:159], v215 offset:6144
	ds_read_b64_tr_b16 v[84:85], v183 offset:28672
	ds_read_b64_tr_b16 v[86:87], v183 offset:29184
	v_mfma_f32_32x32x16_bf16 v[96:111], v[144:147], v[252:255], v[96:111]
	v_add_f32_e32 v251, v78, v251
	v_add_f32_e32 v251, v79, v251
	v_cvt_pk_bf16_f32 v130, v76, v77
	v_cvt_pk_bf16_f32 v131, v78, v79
	ds_read_b128 v[144:147], v215 offset:6656
	ds_read_b64_tr_b16 v[88:89], v183 offset:32768
	ds_read_b64_tr_b16 v[90:91], v183 offset:33280
	s_waitcnt lgkmcnt(6)
	v_mfma_f32_32x32x16_bf16 v[16:31], v[140:143], v[80:83], v[16:31]
	ds_read_b64_tr_b16 v[92:93], v183 offset:36864
	ds_read_b64_tr_b16 v[94:95], v183 offset:37376
	v_max3_f32 v76, v112, v113, v114
	v_max3_f32 v76, v76, v115, v116
	v_max3_f32 v76, v76, v117, v118
	v_max3_f32 v76, v76, v119, v120
	v_max3_f32 v76, v76, v121, v122
	v_max3_f32 v76, v76, v123, v124
	s_waitcnt lgkmcnt(5)
	v_mfma_f32_32x32x16_bf16 v[48:63], v[140:143], v[84:87], v[48:63]
	ds_read_b64_tr_b16 v[64:65], v183 offset:25600
	ds_read_b64_tr_b16 v[66:67], v183 offset:26112
	v_max3_f32 v76, v76, v125, v126
	v_max3_f32 v76, v76, v127, v127
	v_max3_f32 v77, v96, v97, v98
	v_max3_f32 v77, v77, v99, v100
	v_max3_f32 v77, v77, v101, v102
	v_max3_f32 v77, v77, v103, v104
	s_waitcnt lgkmcnt(4)
	v_mfma_f32_32x32x16_bf16 v[32:47], v[140:143], v[88:91], v[32:47]
	ds_read_b64_tr_b16 v[68:69], v183 offset:29696
	ds_read_b64_tr_b16 v[70:71], v183 offset:30208
	v_max3_f32 v77, v77, v105, v106
	v_max3_f32 v77, v77, v107, v108
	v_max3_f32 v77, v77, v109, v110
	v_max3_f32 v77, v77, v111, v111
	v_max_f32_e32 v76, v76, v77
	v_mov_b32_e32 v77, v76
	s_waitcnt lgkmcnt(4)
	v_mfma_f32_32x32x16_bf16 v[0:15], v[140:143], v[92:95], v[0:15]
	ds_read_b64_tr_b16 v[80:81], v183 offset:33792
	ds_read_b64_tr_b16 v[82:83], v183 offset:34304
	v_permlane32_swap_b32_e32 v76, v77
	v_max_f32_e32 v77, v77, v77
	v_max_f32_e32 v76, v76, v76
	v_max_f32_e32 v76, v76, v77
	v_cmp_lt_f32_e32 vcc, s85, v76
	s_cmp_lg_u64 vcc, 0
	v_add_f32_e32 v214, v214, v251
	s_cselect_b64 s[46:47], -1, 0
	s_cbranch_vccnz .LBB5_830

.LBB5_825:
	s_add_i32 s24, s3, 0x2000
	s_cmpk_lg_i32 s3, 0x4000
	s_cselect_b32 s25, s24, 0
	s_lshl_b32 s24, s33, 1
	v_add_u32_e32 v213, s24, v212
	v_add_u32_e32 v215, s25, v208
	v_add_f32_e32 v251, v112, v113
	v_mfma_f32_32x32x16_bf16 v[80:95], v[172:175], v[236:239], v[220:235]
	s_add_i32 s24, s3, s64
	s_mov_b32 m0, s24
	v_add_f32_e32 v251, v114, v251
	global_load_lds_dwordx4 v[198:199], off
	v_add_f32_e32 v251, v115, v251
	v_add_f32_e32 v251, v116, v251
	v_add_f32_e32 v251, v117, v251
	v_cvt_pk_bf16_f32 v140, v112, v113
	v_cvt_pk_bf16_f32 v141, v114, v115
	ds_read_b128 v[172:175], v215
	v_mfma_f32_32x32x16_bf16 v[64:79], v[160:163], v[236:239], v[220:235]
	s_lshl_b32 s24, s25, 1
	s_add_i32 s24, s24, s66
	s_mov_b32 m0, s24
	v_add_f32_e32 v251, v118, v251
	global_load_lds_dwordx4 v[196:197], off
	v_add_f32_e32 v251, v119, v251
	v_add_f32_e32 v251, v120, v251
	v_add_f32_e32 v251, v121, v251
	v_cvt_pk_bf16_f32 v142, v116, v117
	v_cvt_pk_bf16_f32 v143, v118, v119
	ds_read_b128 v[160:163], v215 offset:512
	v_mfma_f32_32x32x16_bf16 v[80:95], v[168:171], v[240:243], v[80:95]
	s_addk_i32 s24, 0x2000
	s_mov_b32 m0, s24
	v_add_f32_e32 v251, v122, v251
	global_load_lds_dwordx4 v[194:195], off
	v_add_f32_e32 v251, v123, v251
	v_add_f32_e32 v251, v124, v251
	v_add_f32_e32 v251, v125, v251
	v_cvt_pk_bf16_f32 v136, v120, v121
	v_cvt_pk_bf16_f32 v137, v122, v123
	ds_read_b128 v[168:171], v215 offset:2048
	v_mfma_f32_32x32x16_bf16 v[64:79], v[152:155], v[240:243], v[64:79]
	v_add_f32_e32 v251, v126, v251
	v_add_f32_e32 v251, v127, v251
	v_add_f32_e32 v251, v96, v251
	v_add_f32_e32 v251, v97, v251
	v_cvt_pk_bf16_f32 v138, v124, v125
	v_cvt_pk_bf16_f32 v139, v126, v127
	ds_read_b128 v[152:155], v215 offset:2560
	v_mfma_f32_32x32x16_bf16 v[80:95], v[164:167], v[244:247], v[80:95]
	v_add_f32_e32 v251, v98, v251
	v_add_f32_e32 v251, v99, v251
	v_add_f32_e32 v251, v100, v251
	v_add_f32_e32 v251, v101, v251
	v_cvt_pk_bf16_f32 v132, v96, v97
	v_cvt_pk_bf16_f32 v133, v98, v99
	ds_read_b128 v[164:167], v215 offset:4096
	v_mfma_f32_32x32x16_bf16 v[64:79], v[148:151], v[244:247], v[64:79]
	v_add_f32_e32 v251, v102, v251
	v_add_f32_e32 v251, v103, v251
	v_add_f32_e32 v251, v104, v251
	v_add_f32_e32 v251, v105, v251
	v_cvt_pk_bf16_f32 v134, v100, v101
	v_cvt_pk_bf16_f32 v135, v102, v103
	ds_read_b128 v[148:151], v215 offset:4608
	ds_read_b64_tr_b16 v[112:113], v213 offset:24576
	ds_read_b64_tr_b16 v[114:115], v213 offset:25088
	v_mfma_f32_32x32x16_bf16 v[80:95], v[156:159], v[252:255], v[80:95]
	v_add_f32_e32 v251, v106, v251
	v_add_f32_e32 v251, v107, v251
	v_add_f32_e32 v251, v108, v251
	v_add_f32_e32 v251, v109, v251
	v_cvt_pk_bf16_f32 v128, v104, v105
	v_cvt_pk_bf16_f32 v129, v106, v107
	ds_read_b128 v[156:159], v215 offset:6144
	ds_read_b64_tr_b16 v[116:117], v213 offset:28672
	ds_read_b64_tr_b16 v[118:119], v213 offset:29184
	v_mfma_f32_32x32x16_bf16 v[64:79], v[144:147], v[252:255], v[64:79]
	v_add_f32_e32 v251, v110, v251
	v_add_f32_e32 v251, v111, v251
	v_cvt_pk_bf16_f32 v130, v108, v109
	v_cvt_pk_bf16_f32 v131, v110, v111
	ds_read_b128 v[144:147], v215 offset:6656
	ds_read_b64_tr_b16 v[120:121], v213 offset:32768
	ds_read_b64_tr_b16 v[122:123], v213 offset:33280
	s_waitcnt lgkmcnt(6)
	v_mfma_f32_32x32x16_bf16 v[16:31], v[140:143], v[112:115], v[16:31]
	ds_read_b64_tr_b16 v[124:125], v213 offset:36864
	ds_read_b64_tr_b16 v[126:127], v213 offset:37376
	v_max3_f32 v108, v80, v81, v82
	v_max3_f32 v108, v108, v83, v84
	v_max3_f32 v108, v108, v85, v86
	v_max3_f32 v108, v108, v87, v88
	v_max3_f32 v108, v108, v89, v90
	v_max3_f32 v108, v108, v91, v92
	s_waitcnt lgkmcnt(5)
	v_mfma_f32_32x32x16_bf16 v[48:63], v[140:143], v[116:119], v[48:63]
	ds_read_b64_tr_b16 v[96:97], v213 offset:25600
	ds_read_b64_tr_b16 v[98:99], v213 offset:26112
	v_max3_f32 v108, v108, v93, v94
	v_max3_f32 v108, v108, v95, v95
	v_max3_f32 v109, v64, v65, v66
	v_max3_f32 v109, v109, v67, v68
	v_max3_f32 v109, v109, v69, v70
	v_max3_f32 v109, v109, v71, v72
	s_waitcnt lgkmcnt(4)
	v_mfma_f32_32x32x16_bf16 v[32:47], v[140:143], v[120:123], v[32:47]
	ds_read_b64_tr_b16 v[100:101], v213 offset:29696
	ds_read_b64_tr_b16 v[102:103], v213 offset:30208
	v_max3_f32 v109, v109, v73, v74
	v_max3_f32 v109, v109, v75, v76
	v_max3_f32 v109, v109, v77, v78
	v_max3_f32 v109, v109, v79, v79
	v_max_f32_e32 v108, v108, v109
	v_mov_b32_e32 v109, v108
	s_waitcnt lgkmcnt(4)
	v_mfma_f32_32x32x16_bf16 v[0:15], v[140:143], v[124:127], v[0:15]
	ds_read_b64_tr_b16 v[112:113], v213 offset:33792
	ds_read_b64_tr_b16 v[114:115], v213 offset:34304
	v_permlane32_swap_b32_e32 v108, v109
	v_max_f32_e32 v109, v109, v109
	v_max_f32_e32 v108, v108, v108
	v_max_f32_e32 v108, v108, v109
	v_cmp_lt_f32_e32 vcc, s85, v108
	s_cmp_lg_u64 vcc, 0
	v_add_f32_e32 v214, v214, v251
	s_cselect_b64 s[46:47], -1, 0
	s_cbranch_vccnz .LBB5_833
